# P9 sample row pass folded into P8 (run by the 32 split-K GEMM workgroups after a 16-workgroup counter sync); seam before P9 removed
# baseline (speedup 1.0000x reference)
; #define PH(k) if (a.ph_lo <= (k) && (k) < a.ph_hi) { if ((k) > a.ph_lo && (k) != 6) SEAM(k);
; __global__ void __launch_bounds__(512) fwd_kernel(Args a) {
;     ...
;     PH(9) { row_pass1(a, MP, MT, gw, NGW, lane); } PHEND
.LBB0_1079:
	s_cmp_lt_i32 s56, 10
	s_cselect_b64 s[6:7], -1, 0
	s_cmp_gt_i32 s57, 9
	s_cselect_b64 s[0:1], -1, 0
	s_and_b64 s[0:1], s[6:7], s[0:1]
	s_andn2_b64 vcc, exec, s[0:1]
	s_cbranch_vccnz .LBB0_1139
	s_cmp_lt_i32 s2, 32
	s_cbranch_scc0 .LBB0_1139
	v_cmp_eq_u32_e32 vcc, 0, v178
	s_and_saveexec_b64 s[0:1], vcc
	s_cbranch_execz .Lp9m_join
	s_add_u32 s98, s54, 0x22a4480
	s_addc_u32 s99, s55, 0
	v_mov_b32_e32 v0, 0
	s_cmp_lt_i32 s2, 16
	s_cbranch_scc0 .Lp9m_spin
	buffer_wbl2 sc1
	s_waitcnt vmcnt(0)
	v_mov_b32_e32 v1, 1
	global_atomic_add v0, v1, s[98:99]
.Lp9m_spin:
	global_load_dword v1, v0, s[98:99] sc1
	s_waitcnt vmcnt(0)
	v_cmp_lt_u32_e32 vcc, 15, v1
	s_cbranch_vccnz .Lp9m_go
	s_sleep 1
	s_branch .Lp9m_spin

; __device__ __forceinline__ unsigned xb_ld(unsigned* p)              { return __hip_atomic_load(p, __ATOMIC_RELAXED, __HIP_MEMORY_SCOPE_AGENT); }
; __device__ __forceinline__ unsigned xb_add(unsigned* p, unsigned v) { return __hip_atomic_fetch_add(p, v, __ATOMIC_RELAXED, __HIP_MEMORY_SCOPE_AGENT); }
; #define XB_SPIN(cond, bar) do { unsigned _sp = 0; while (cond) { __builtin_amdgcn_s_sleep(1); \
;     if ((++_sp & 255u) == 0u) { if (xb_ld(&(bar)[XB_TMO])) break; if (_sp > XB_SPIN_CAP) { atomicAdd(&(bar)[XB_TMO], 1u); break; } } } } while (0)
; __device__ __forceinline__ void xcd_barrier(const XcdBarrier& b) {
;     asm volatile("s_waitcnt vmcnt(0)" ::: "memory");
;     __syncthreads();
;     if (threadIdx.x == 0) {
;         unsigned* bar = b.bar;
;         __builtin_amdgcn_s_waitcnt(0);
;         unsigned nloc = b.st[0], nx = b.st[1];
;         if (nloc == 0u) { xcd_barrier_complete(bar, b.x, nloc, nx); b.st[0] = nloc; b.st[1] = nx; }
;         const unsigned old = xb_add(&bar[XB_XSUB(b.x)], 1u);
;         const unsigned gen = old / nloc;
;         if (old + 1u == (gen + 1u) * nloc) {
;             __builtin_amdgcn_fence(__ATOMIC_RELEASE, "agent");
;             asm volatile("s_waitcnt vmcnt(0)" ::: "memory");
;             const unsigned og = xb_add(&bar[XB_TOP], 1u);
;             const unsigned tg = og / nx;
;             if (og + 1u == (tg + 1u) * nx) xb_add(&bar[XB_TOPGEN], 1u);
;             else XB_SPIN(xb_ld(&bar[XB_TOPGEN]) == tg, bar);
;             __builtin_amdgcn_fence(__ATOMIC_ACQUIRE, "agent");
;             xb_add(&bar[XB_XGEN(b.x)], 1u);
;             asm volatile("s_waitcnt vmcnt(0)" ::: "memory");
;         } else {
;             XB_SPIN(xb_ld(&bar[XB_XGEN(b.x)]) == gen, bar);
;             __builtin_amdgcn_fence(__ATOMIC_ACQUIRE, "agent");
;             asm volatile("s_waitcnt vmcnt(0)" ::: "memory");
;         }
;     }
;     __syncthreads();
; }
.Lp9m_join:
	s_or_b64 exec, exec, s[0:1]
	s_barrier
	s_branch .LBB0_1134
	s_getreg_b32 s3, hwreg(HW_REG_XCC_ID, 0, 4)
	s_waitcnt vmcnt(0)
	v_cmp_eq_u32_e32 vcc, 0, v178
	s_waitcnt vmcnt(0) lgkmcnt(0)
	s_barrier
	s_and_saveexec_b64 s[0:1], vcc
	s_cbranch_execz .LBB0_1133
	s_add_i32 s4, 0, 0x23ff0
	v_mov_b32_e32 v0, s4
	s_waitcnt vmcnt(0) expcnt(0) lgkmcnt(0)
	ds_read_b32 v2, v0
	s_add_i32 s4, 0, 0x23ff4
	v_mov_b32_e32 v0, s4
	ds_read_b32 v0, v0
	s_and_b32 s3, s3, 15
	s_waitcnt lgkmcnt(1)
	v_cmp_ne_u32_e32 vcc, 0, v2
	s_cbranch_vccnz .LBB0_1097
	v_readlane_b32 s4, v252, 0
	s_mul_i32 s33, s4, s58
	s_add_u32 s4, s54, 0x22a2200
	s_addc_u32 s5, s55, 0
	s_add_u32 s8, s54, 0x22a2400
	s_addc_u32 s9, s55, 0
	s_add_u32 s10, s54, 0x22a2500
	s_addc_u32 s11, s55, 0
	s_add_u32 s14, s54, 0x22a2600
	s_addc_u32 s15, s55, 0
	s_add_u32 s16, s54, 0x22a2700
	s_addc_u32 s17, s55, 0
	s_add_u32 s18, s54, 0x22a2800
	s_addc_u32 s19, s55, 0
	s_add_u32 s20, s54, 0x22a2900
	s_addc_u32 s21, s55, 0
	s_add_u32 s22, s54, 0x22a2a00
	s_addc_u32 s23, s55, 0
	s_add_u32 s24, s54, 0x22a2b00
	s_addc_u32 s25, s55, 0
	s_add_u32 s26, s54, 0x22a2c00
	s_addc_u32 s27, s55, 0
	s_add_u32 s28, s54, 0x22a2d00
	s_addc_u32 s29, s55, 0
	s_add_u32 s30, s54, 0x22a2e00
	s_addc_u32 s31, s55, 0
	s_add_u32 s34, s54, 0x22a2f00
	s_addc_u32 s35, s55, 0
	s_add_u32 s40, s54, 0x22a3000
	s_addc_u32 s41, s55, 0
	s_add_u32 s42, s54, 0x22a3100
	s_addc_u32 s43, s55, 0
	s_add_u32 s44, s54, 0x22a3200
	s_addc_u32 s45, s55, 0
	s_add_u32 s46, s54, 0x22a3300
	s_mul_i32 s33, s33, s59
	s_addc_u32 s47, s55, 0
	s_mov_b32 s66, 1
	v_mov_b32_e32 v16, 0
	s_branch .LBB0_1085

; #define PH(k) if (a.ph_lo <= (k) && (k) < a.ph_hi) { if ((k) > a.ph_lo && (k) != 6) SEAM(k);
; __device__ __forceinline__ void row_pass1(const Args& a, int row_lo, int row_hi, int gw, int NGW, int lane) {
;     const bf16_t* Y = (const bf16_t*)(a.ws + A_GB); bf16_t* A2 = (bf16_t*)(a.ws + A_RB); const float* rss = (const float*)(a.ws + WS_RSS1); float* XO = a.out + O_Y;
;     f32x4 gp[4], gq[4];
; #pragma unroll
;     for (int j = 0; j < 4; ++j) { gp[j] = ((const f32x4*)a.in[I_NMPOST])[lane + 64 * j]; gq[j] = ((const f32x4*)a.in[I_NFPRE])[lane + 64 * j]; }
;     for (int r0 = row_lo + 2 * gw; r0 < row_hi; r0 += 2 * NGW) {
;         f32x4 xv[2][4]; u32x2 yv[2][4]; float rs[2];
; #pragma unroll
;         for (int r = 0; r < 2; ++r) { const int row = (r0 + r < row_hi) ? r0 + r : r0; rs[r] = rss[row];
;             const f32x4* xr = (const f32x4*)xrow_ptr(a, row) + lane; const u32x2* yr = (const u32x2*)(Y + (size_t)row * DM) + lane;
; #pragma unroll
;             for (int j = 0; j < 4; ++j) { xv[r][j] = xr[64 * j]; yv[r][j] = yr[64 * j]; } }
; __global__ void __launch_bounds__(512) fwd_kernel(Args a) {
;     ...
;     PH(9) { row_pass1(a, MP, MT, gw, NGW, lane); } PHEND
.LBB0_1134:
	s_cmpk_gt_i32 s81, 0x1ff
	s_cbranch_scc1 .LBB0_1139
	v_readlane_b32 s16, v252, 1
	v_readlane_b32 s20, v252, 5
	v_readlane_b32 s21, v252, 6
	v_readlane_b32 s22, v252, 7
	v_readlane_b32 s23, v252, 8
	v_readlane_b32 s28, v252, 13
	v_readlane_b32 s29, v252, 14
	s_waitcnt vmcnt(0)
	v_lshlrev_b32_e32 v48, 4, v176
	v_readlane_b32 s30, v252, 15
	v_readlane_b32 s31, v252, 16
	s_mov_b64 s[20:21], s[28:29]
	s_mov_b64 s[22:23], s[30:31]
	global_load_dwordx4 v[0:3], v48, s[20:21]
	s_waitcnt lgkmcnt(0)
	global_load_dwordx4 v[4:7], v48, s[22:23]
	global_load_dwordx4 v[8:11], v48, s[20:21] offset:1024
	global_load_dwordx4 v[12:15], v48, s[22:23] offset:1024
	global_load_dwordx4 v[16:19], v48, s[20:21] offset:2048
	global_load_dwordx4 v[20:23], v48, s[22:23] offset:2048
	global_load_dwordx4 v[24:27], v48, s[20:21] offset:3072
	global_load_dwordx4 v[28:31], v48, s[22:23] offset:3072
	v_mov_b32_e32 v49, 0
	v_lshlrev_b32_e32 v32, 3, v176
	v_mov_b32_e32 v33, v49
	v_lshl_add_u64 v[34:35], s[54:55], 0, v[32:33]
	v_mbcnt_lo_u32_b32 v33, -1, 0
	s_mov_b64 s[0:1], 0xde00000
	v_mbcnt_hi_u32_b32 v33, -1, v33
	v_lshl_add_u64 v[50:51], v[34:35], 0, s[0:1]
	v_and_b32_e32 v34, 64, v33
	v_add_u32_e32 v34, 64, v34
	v_xor_b32_e32 v35, 32, v33
	v_cmp_lt_i32_e32 vcc, v35, v34
	v_readlane_b32 s18, v252, 3
	v_readlane_b32 s19, v252, 4
	v_cndmask_b32_e32 v35, v33, v35, vcc
	v_lshlrev_b32_e32 v66, 2, v35
	v_xor_b32_e32 v35, 16, v33
	v_cmp_lt_i32_e32 vcc, v35, v34
	s_add_u32 s18, s54, 0x2280000
	s_addc_u32 s19, s55, 0
	v_cndmask_b32_e32 v35, v33, v35, vcc
	v_lshlrev_b32_e32 v67, 2, v35
	v_xor_b32_e32 v35, 8, v33
	v_cmp_lt_i32_e32 vcc, v35, v34
	s_lshl_b32 s20, s81, 1
	s_add_i32 s4, s20, 0x4000
	v_cndmask_b32_e32 v35, v33, v35, vcc
	v_lshlrev_b32_e32 v68, 2, v35
	v_xor_b32_e32 v35, 4, v33
	v_cmp_lt_i32_e32 vcc, v35, v34
	s_ashr_i32 s5, s4, 31
	s_movk_i32 s8, 0x200
	v_cndmask_b32_e32 v35, v33, v35, vcc
	v_lshlrev_b32_e32 v69, 2, v35
	v_xor_b32_e32 v35, 2, v33
	v_cmp_lt_i32_e32 vcc, v35, v34
	s_lshl_b64 s[0:1], s[4:5], 12
	s_add_u32 s0, s52, s0
	v_cndmask_b32_e32 v35, v33, v35, vcc
	v_lshlrev_b32_e32 v70, 2, v35
	v_xor_b32_e32 v35, 1, v33
	v_cmp_lt_i32_e32 vcc, v35, v34
	s_addc_u32 s1, s53, s1
	s_ashr_i32 s9, s8, 31
	v_cndmask_b32_e32 v33, v33, v35, vcc
	v_lshl_add_u64 v[34:35], s[0:1], 0, v[48:49]
	s_mov_b64 s[0:1], 0x1000
	v_lshl_add_u64 v[52:53], v[34:35], 0, s[0:1]
	s_lshl_b64 s[0:1], s[4:5], 11
	s_lshl_b64 s[10:11], s[8:9], 12
	v_or_b32_e32 v54, s0, v32
	v_mov_b32_e32 v55, s1
	s_lshl_b64 s[14:15], s[8:9], 11
	s_lshl_b64 s[0:1], s[4:5], 2
	v_readlane_b32 s17, v252, 2
	v_readlane_b32 s24, v252, 9
	v_readlane_b32 s25, v252, 10
	s_add_u32 s21, s0, 0x2280000
	v_lshlrev_b32_e32 v71, 2, v33
	s_addc_u32 s22, s1, 0
	s_lshl_b64 s[16:17], s[8:9], 2
	v_lshlrev_b32_e32 v48, 4, v176
	s_mov_b32 s23, 0xde00000
	v_mov_b32_e32 v72, 0x358637bd
	s_mov_b32 s24, 0x800000
	s_mov_b32 s25, 0x9a00000
	v_readlane_b32 s26, v252, 11
	v_readlane_b32 s27, v252, 12
	s_branch .LBB0_1137

; __device__ __forceinline__ unsigned xb_ld(unsigned* p)              { return __hip_atomic_load(p, __ATOMIC_RELAXED, __HIP_MEMORY_SCOPE_AGENT); }
; __device__ __forceinline__ unsigned xb_add(unsigned* p, unsigned v) { return __hip_atomic_fetch_add(p, v, __ATOMIC_RELAXED, __HIP_MEMORY_SCOPE_AGENT); }
; #define XB_SPIN(cond, bar) do { unsigned _sp = 0; while (cond) { __builtin_amdgcn_s_sleep(1); \
;     if ((++_sp & 255u) == 0u) { if (xb_ld(&(bar)[XB_TMO])) break; if (_sp > XB_SPIN_CAP) { atomicAdd(&(bar)[XB_TMO], 1u); break; } } } } while (0)
; __device__ __forceinline__ void xcd_barrier(const XcdBarrier& b) {
;     asm volatile("s_waitcnt vmcnt(0)" ::: "memory");
;     __syncthreads();
;     if (threadIdx.x == 0) {
;         unsigned* bar = b.bar;
;         __builtin_amdgcn_s_waitcnt(0);
;         unsigned nloc = b.st[0], nx = b.st[1];
;         if (nloc == 0u) { xcd_barrier_complete(bar, b.x, nloc, nx); b.st[0] = nloc; b.st[1] = nx; }
;         const unsigned old = xb_add(&bar[XB_XSUB(b.x)], 1u);
;         const unsigned gen = old / nloc;
;         if (old + 1u == (gen + 1u) * nloc) {
;             __builtin_amdgcn_fence(__ATOMIC_RELEASE, "agent");
;             asm volatile("s_waitcnt vmcnt(0)" ::: "memory");
;             const unsigned og = xb_add(&bar[XB_TOP], 1u);
;             const unsigned tg = og / nx;
;             if (og + 1u == (tg + 1u) * nx) xb_add(&bar[XB_TOPGEN], 1u);
;             else XB_SPIN(xb_ld(&bar[XB_TOPGEN]) == tg, bar);
;             __builtin_amdgcn_fence(__ATOMIC_ACQUIRE, "agent");
;             xb_add(&bar[XB_XGEN(b.x)], 1u);
;             asm volatile("s_waitcnt vmcnt(0)" ::: "memory");
.LBB0_1139:
	s_cmp_lt_i32 s56, 11
	s_cselect_b64 s[4:5], -1, 0
	s_cmp_gt_i32 s57, 10
	s_cselect_b64 s[0:1], -1, 0
	s_and_b64 s[0:1], s[4:5], s[0:1]
	s_andn2_b64 vcc, exec, s[0:1]
	s_cbranch_vccnz .LBB0_1210
	s_andn2_b64 vcc, exec, s[6:7]
	s_cbranch_vccnz .LBB0_1194
	s_getreg_b32 s3, hwreg(HW_REG_XCC_ID, 0, 4)
	s_waitcnt vmcnt(0)
	v_cmp_eq_u32_e32 vcc, 0, v178
	s_waitcnt vmcnt(0) lgkmcnt(0)
	s_barrier
	s_and_saveexec_b64 s[0:1], vcc
	s_cbranch_execz .LBB0_1193
	buffer_inv sc1
	v_mov_b32_e32 v0, 0x23ff0
	ds_read2_b32 v[0:1], v0 offset1:1
	s_and_b32 s98, s3, 15
	s_lshl_b32 s98, s98, 8
	s_add_u32 s98, s54, s98
	s_addc_u32 s99, s55, 0
	s_add_u32 s98, s98, 0x22a3400
	s_addc_u32 s99, s99, 0
	v_mov_b32_e32 v2, 0
	v_mov_b32_e32 v3, 1
	global_atomic_add v4, v2, v3, s[98:99] sc0
	s_add_u32 s100, s54, 0x22a5400
	s_addc_u32 s101, s55, 0
	s_waitcnt vmcnt(0) lgkmcnt(0)
	v_mul_u32_u24_e32 v0, 8, v0
	v_mul_u32_u24_e32 v1, 8, v1
	v_add_u32_e32 v4, 1, v4
	v_cmp_eq_u32_e32 vcc, v4, v0
	s_cbranch_vccz .Lxb_poll_s8
	buffer_wbl2 sc1
	s_waitcnt vmcnt(0)
	global_atomic_add v2, v3, s[100:101]

; __device__ __forceinline__ unsigned xb_ld(unsigned* p)              { return __hip_atomic_load(p, __ATOMIC_RELAXED, __HIP_MEMORY_SCOPE_AGENT); }
; __device__ __forceinline__ unsigned xb_add(unsigned* p, unsigned v) { return __hip_atomic_fetch_add(p, v, __ATOMIC_RELAXED, __HIP_MEMORY_SCOPE_AGENT); }
; #define XB_SPIN(cond, bar) do { unsigned _sp = 0; while (cond) { __builtin_amdgcn_s_sleep(1); \
;     if ((++_sp & 255u) == 0u) { if (xb_ld(&(bar)[XB_TMO])) break; if (_sp > XB_SPIN_CAP) { atomicAdd(&(bar)[XB_TMO], 1u); break; } } } } while (0)
; __device__ __forceinline__ void xcd_barrier(const XcdBarrier& b) {
;     asm volatile("s_waitcnt vmcnt(0)" ::: "memory");
;     __syncthreads();
;     if (threadIdx.x == 0) {
;         unsigned* bar = b.bar;
;         __builtin_amdgcn_s_waitcnt(0);
;         unsigned nloc = b.st[0], nx = b.st[1];
;         if (nloc == 0u) { xcd_barrier_complete(bar, b.x, nloc, nx); b.st[0] = nloc; b.st[1] = nx; }
;         const unsigned old = xb_add(&bar[XB_XSUB(b.x)], 1u);
;         const unsigned gen = old / nloc;
;         if (old + 1u == (gen + 1u) * nloc) {
;             __builtin_amdgcn_fence(__ATOMIC_RELEASE, "agent");
;             asm volatile("s_waitcnt vmcnt(0)" ::: "memory");
;             const unsigned og = xb_add(&bar[XB_TOP], 1u);
;             const unsigned tg = og / nx;
;             if (og + 1u == (tg + 1u) * nx) xb_add(&bar[XB_TOPGEN], 1u);
;             else XB_SPIN(xb_ld(&bar[XB_TOPGEN]) == tg, bar);
;             __builtin_amdgcn_fence(__ATOMIC_ACQUIRE, "agent");
;             xb_add(&bar[XB_XGEN(b.x)], 1u);
;             asm volatile("s_waitcnt vmcnt(0)" ::: "memory");
.LBB0_1210:
	s_cmp_lt_i32 s56, 12
	s_cselect_b64 s[10:11], -1, 0
	s_cmp_gt_i32 s57, 11
	s_cselect_b64 s[0:1], -1, 0
	s_and_b64 s[0:1], s[10:11], s[0:1]
	s_andn2_b64 vcc, exec, s[0:1]
	s_cbranch_vccnz .LBB0_1307
	s_andn2_b64 vcc, exec, s[4:5]
	s_cbranch_vccnz .LBB0_1265
	s_getreg_b32 s3, hwreg(HW_REG_XCC_ID, 0, 4)
	s_waitcnt vmcnt(0)
	v_cmp_eq_u32_e32 vcc, 0, v178
	s_waitcnt vmcnt(0) lgkmcnt(0)
	s_barrier
	s_and_saveexec_b64 s[0:1], vcc
	s_cbranch_execz .LBB0_1264
	buffer_inv sc1
	v_mov_b32_e32 v0, 0x23ff0
	ds_read2_b32 v[0:1], v0 offset1:1
	s_and_b32 s98, s3, 15
	s_lshl_b32 s98, s98, 8
	s_add_u32 s98, s54, s98
	s_addc_u32 s99, s55, 0
	s_add_u32 s98, s98, 0x22a3400
	s_addc_u32 s99, s99, 0
	v_mov_b32_e32 v2, 0
	v_mov_b32_e32 v3, 1
	global_atomic_add v4, v2, v3, s[98:99] sc0
	s_add_u32 s100, s54, 0x22a5400
	s_addc_u32 s101, s55, 0
	s_waitcnt vmcnt(0) lgkmcnt(0)
	v_mul_u32_u24_e32 v0, 9, v0
	v_mul_u32_u24_e32 v1, 9, v1
	v_add_u32_e32 v4, 1, v4
	v_cmp_eq_u32_e32 vcc, v4, v0
	s_cbranch_vccz .Lxb_poll_s9
	buffer_wbl2 sc1
	s_waitcnt vmcnt(0)
	global_atomic_add v2, v3, s[100:101]

; __device__ __forceinline__ unsigned xb_ld(unsigned* p)              { return __hip_atomic_load(p, __ATOMIC_RELAXED, __HIP_MEMORY_SCOPE_AGENT); }
; __device__ __forceinline__ unsigned xb_add(unsigned* p, unsigned v) { return __hip_atomic_fetch_add(p, v, __ATOMIC_RELAXED, __HIP_MEMORY_SCOPE_AGENT); }
; #define XB_SPIN(cond, bar) do { unsigned _sp = 0; while (cond) { __builtin_amdgcn_s_sleep(1); \
;     if ((++_sp & 255u) == 0u) { if (xb_ld(&(bar)[XB_TMO])) break; if (_sp > XB_SPIN_CAP) { atomicAdd(&(bar)[XB_TMO], 1u); break; } } } } while (0)
; __device__ __forceinline__ void xcd_barrier(const XcdBarrier& b) {
;     asm volatile("s_waitcnt vmcnt(0)" ::: "memory");
;     __syncthreads();
;     if (threadIdx.x == 0) {
;         unsigned* bar = b.bar;
;         __builtin_amdgcn_s_waitcnt(0);
;         unsigned nloc = b.st[0], nx = b.st[1];
;         if (nloc == 0u) { xcd_barrier_complete(bar, b.x, nloc, nx); b.st[0] = nloc; b.st[1] = nx; }
;         const unsigned old = xb_add(&bar[XB_XSUB(b.x)], 1u);
;         const unsigned gen = old / nloc;
;         if (old + 1u == (gen + 1u) * nloc) {
;             __builtin_amdgcn_fence(__ATOMIC_RELEASE, "agent");
;             asm volatile("s_waitcnt vmcnt(0)" ::: "memory");
;             const unsigned og = xb_add(&bar[XB_TOP], 1u);
;             const unsigned tg = og / nx;
;             if (og + 1u == (tg + 1u) * nx) xb_add(&bar[XB_TOPGEN], 1u);
;             else XB_SPIN(xb_ld(&bar[XB_TOPGEN]) == tg, bar);
;             __builtin_amdgcn_fence(__ATOMIC_ACQUIRE, "agent");
;             xb_add(&bar[XB_XGEN(b.x)], 1u);
;             asm volatile("s_waitcnt vmcnt(0)" ::: "memory");
.LBB0_1307:
	s_cmp_lt_i32 s56, 13
	s_cselect_b64 s[6:7], -1, 0
	s_cmp_gt_i32 s57, 12
	s_cselect_b64 s[0:1], -1, 0
	s_and_b64 s[0:1], s[6:7], s[0:1]
	s_andn2_b64 vcc, exec, s[0:1]
	s_cbranch_vccnz .LBB0_1460
	s_andn2_b64 vcc, exec, s[10:11]
	s_cbranch_vccnz .LBB0_1362
	s_getreg_b32 s3, hwreg(HW_REG_XCC_ID, 0, 4)
	s_waitcnt vmcnt(0)
	v_cmp_eq_u32_e32 vcc, 0, v178
	s_waitcnt vmcnt(0) lgkmcnt(0)
	s_barrier
	s_and_saveexec_b64 s[0:1], vcc
	s_cbranch_execz .LBB0_1361
	buffer_inv sc1
	v_mov_b32_e32 v0, 0x23ff0
	ds_read2_b32 v[0:1], v0 offset1:1
	s_and_b32 s98, s3, 15
	s_lshl_b32 s98, s98, 8
	s_add_u32 s98, s54, s98
	s_addc_u32 s99, s55, 0
	s_add_u32 s98, s98, 0x22a3400
	s_addc_u32 s99, s99, 0
	v_mov_b32_e32 v2, 0
	v_mov_b32_e32 v3, 1
	global_atomic_add v4, v2, v3, s[98:99] sc0
	s_add_u32 s100, s54, 0x22a5400
	s_addc_u32 s101, s55, 0
	s_waitcnt vmcnt(0) lgkmcnt(0)
	v_mul_u32_u24_e32 v0, 10, v0
	v_mul_u32_u24_e32 v1, 10, v1
	v_add_u32_e32 v4, 1, v4
	v_cmp_eq_u32_e32 vcc, v4, v0
	s_cbranch_vccz .Lxb_poll_s10
	buffer_wbl2 sc1
	s_waitcnt vmcnt(0)
	global_atomic_add v2, v3, s[100:101]

; __device__ __forceinline__ unsigned xb_ld(unsigned* p)              { return __hip_atomic_load(p, __ATOMIC_RELAXED, __HIP_MEMORY_SCOPE_AGENT); }
; __device__ __forceinline__ unsigned xb_add(unsigned* p, unsigned v) { return __hip_atomic_fetch_add(p, v, __ATOMIC_RELAXED, __HIP_MEMORY_SCOPE_AGENT); }
; #define XB_SPIN(cond, bar) do { unsigned _sp = 0; while (cond) { __builtin_amdgcn_s_sleep(1); \
;     if ((++_sp & 255u) == 0u) { if (xb_ld(&(bar)[XB_TMO])) break; if (_sp > XB_SPIN_CAP) { atomicAdd(&(bar)[XB_TMO], 1u); break; } } } } while (0)
; __device__ __forceinline__ void xcd_barrier(const XcdBarrier& b) {
;     asm volatile("s_waitcnt vmcnt(0)" ::: "memory");
;     __syncthreads();
;     if (threadIdx.x == 0) {
;         unsigned* bar = b.bar;
;         __builtin_amdgcn_s_waitcnt(0);
;         unsigned nloc = b.st[0], nx = b.st[1];
;         if (nloc == 0u) { xcd_barrier_complete(bar, b.x, nloc, nx); b.st[0] = nloc; b.st[1] = nx; }
;         const unsigned old = xb_add(&bar[XB_XSUB(b.x)], 1u);
;         const unsigned gen = old / nloc;
;         if (old + 1u == (gen + 1u) * nloc) {
;             __builtin_amdgcn_fence(__ATOMIC_RELEASE, "agent");
;             asm volatile("s_waitcnt vmcnt(0)" ::: "memory");
;             const unsigned og = xb_add(&bar[XB_TOP], 1u);
;             const unsigned tg = og / nx;
;             if (og + 1u == (tg + 1u) * nx) xb_add(&bar[XB_TOPGEN], 1u);
;             else XB_SPIN(xb_ld(&bar[XB_TOPGEN]) == tg, bar);
;             __builtin_amdgcn_fence(__ATOMIC_ACQUIRE, "agent");
;             xb_add(&bar[XB_XGEN(b.x)], 1u);
;             asm volatile("s_waitcnt vmcnt(0)" ::: "memory");
;         } else {
;             XB_SPIN(xb_ld(&bar[XB_XGEN(b.x)]) == gen, bar);
;             __builtin_amdgcn_fence(__ATOMIC_ACQUIRE, "agent");
;             asm volatile("s_waitcnt vmcnt(0)" ::: "memory");
;         }
;     }
;     __syncthreads();
; }
.LBB0_1460:
	s_cmp_lt_i32 s56, 14
	s_cselect_b64 s[0:1], -1, 0
	s_cmp_gt_i32 s57, 13
	s_cselect_b64 s[4:5], -1, 0
	s_and_b64 s[0:1], s[0:1], s[4:5]
	s_andn2_b64 vcc, exec, s[0:1]
	s_cbranch_vccnz .LBB0_1520
	s_andn2_b64 vcc, exec, s[6:7]
	s_cbranch_vccnz .LBB0_1515
	s_getreg_b32 s3, hwreg(HW_REG_XCC_ID, 0, 4)
	s_waitcnt vmcnt(0)
	v_cmp_eq_u32_e32 vcc, 0, v178
	s_waitcnt vmcnt(0) lgkmcnt(0)
	s_barrier
	s_and_saveexec_b64 s[0:1], vcc
	s_cbranch_execz .LBB0_1514
	buffer_inv sc1
	v_mov_b32_e32 v0, 0x23ff0
	ds_read2_b32 v[0:1], v0 offset1:1
	s_and_b32 s98, s3, 15
	s_lshl_b32 s98, s98, 8
	s_add_u32 s98, s54, s98
	s_addc_u32 s99, s55, 0
	s_add_u32 s98, s98, 0x22a3400
	s_addc_u32 s99, s99, 0
	v_mov_b32_e32 v2, 0
	v_mov_b32_e32 v3, 1
	global_atomic_add v4, v2, v3, s[98:99] sc0
	s_add_u32 s100, s54, 0x22a5400
	s_addc_u32 s101, s55, 0
	s_waitcnt vmcnt(0) lgkmcnt(0)
	v_mul_u32_u24_e32 v0, 11, v0
	v_mul_u32_u24_e32 v1, 11, v1
	v_add_u32_e32 v4, 1, v4
	v_cmp_eq_u32_e32 vcc, v4, v0
	s_cbranch_vccz .Lxb_poll_s11
	buffer_wbl2 sc1
	s_waitcnt vmcnt(0)
	global_atomic_add v2, v3, s[100:101]
